# P3 queue order: weight-copy and conv items handed out before the four shortest attention unit ranks so they overlap attention compute
# speedup vs baseline: 1.0072x; 1.0072x over previous
; template<int THRL,class Extra> __device__ __forceinline__ void attn_phase_dyn(char*lds,const AttnTensors&T,unsigned*ctr,const Extra&X,int nextra){
;     ...
;   for(;;){
;     if(tid==0){uw[0]=nxt;}
;     asm volatile("s_waitcnt lgkmcnt(0)\n\ts_barrier":::"memory");
;     const unsigned u=(unsigned)__builtin_amdgcn_readfirstlane((int)uw[0]);
;     if(u>=(unsigned)(BATCH*NHEAD*NQB+nextra))break;
;     if(u>=(unsigned)(BATCH*NHEAD*NQB)){ if(tid==0)nxt=G_+__hip_atomic_fetch_add(ctr,1u,__ATOMIC_RELAXED,__HIP_MEMORY_SCOPE_AGENT);
;       X((int)u-BATCH*NHEAD*NQB); asm volatile("s_waitcnt lgkmcnt(0)\n\ts_barrier":::"memory"); continue; }
;     const int qb=NQB-1-(int)(u/(BATCH*NHEAD)), bh=(int)(u%(BATCH*NHEAD));
.LBB0_343:
	s_and_saveexec_b64 s[6:7], s[18:19]
	ds_write_b32 v201, v213 offset:49152
	s_or_b64 exec, exec, s[6:7]
	s_waitcnt lgkmcnt(0)
	s_barrier
	ds_read_b32 v1, v201 offset:49152
	s_mov_b64 s[6:7], -1
	s_waitcnt lgkmcnt(0)
	v_readfirstlane_b32 s63, v1
	s_cmpk_lt_u32 s63, 0x300
	s_cbranch_scc1 .Lqmap_done
	s_cmpk_gt_u32 s63, 0x57f
	s_cbranch_scc1 .Lqmap_done
	s_add_i32 s80, s63, 0x200
	s_cmpk_lt_u32 s63, 0x380
	s_cbranch_scc1 .Lqmap_set
	s_add_i32 s80, s63, 0x80
	s_cmpk_lt_u32 s63, 0x480
	s_cbranch_scc1 .Lqmap_set
	s_add_i32 s80, s63, 0xfffffe80
.Lqmap_set:
	s_mov_b32 s63, s80
.Lqmap_done:
	s_cmpk_gt_u32 s63, 0x57f
	s_cbranch_scc1 .LBB0_342
	s_cmpk_lt_u32 s63, 0x400
	s_cbranch_scc0 .LBB0_361
	s_and_b32 s6, s63, 63
	s_lshr_b32 s44, s63, 6
	s_lshl_b32 s7, s6, 6
	s_add_i32 s7, s7, 0
	s_lshl_b32 s8, s44, 2
	s_sub_i32 s7, s7, s8
	s_add_i32 s7, s7, 0x1883c
	s_lshl_b32 s12, s6, 14
	v_mov_b32_e32 v1, s7
	s_sub_i32 s7, 15, s44
	v_lshl_add_u64 v[6:7], v[208:209], 0, s[12:13]
	s_bfe_u32 s12, s63, 0x30003
	v_readfirstlane_b32 s66, v0
	s_lshr_b32 s65, s66, 6
	s_lshl_b32 s8, s12, 12
	s_lshl_b32 s45, s7, 8
	s_or_b32 s7, s45, s8
	s_lshl_b32 s69, s65, 5
	s_add_i32 s10, s7, s69
	s_mov_b32 s11, s13
	ds_read_b32 v1, v1
	s_lshl_b64 s[8:9], s[10:11], 10
	s_add_u32 s7, s47, s8
	s_addc_u32 s9, s48, s9
	s_lshl_b32 s8, s63, 6
	s_and_b32 s8, s8, 0x1c0
	s_lshl_b32 s64, s8, 1
	s_waitcnt lgkmcnt(0)
	v_readfirstlane_b32 s6, v1
	s_add_u32 s8, s7, s64
	s_addc_u32 s9, s9, 0
	s_ashr_i32 s7, s6, 31
	s_lshl_b64 s[40:41], s[6:7], 15
	s_lshl_b32 s7, s12, 21
	s_add_u32 s40, s40, s7
	s_addc_u32 s41, s41, 0
	s_lshl_b64 s[40:41], s[40:41], 1
	s_add_u32 s7, s49, s40
	s_addc_u32 s12, s50, s41
	s_add_u32 s42, s7, s64
	s_addc_u32 s43, s12, 0
	s_add_u32 s7, s51, s40
	s_addc_u32 s12, s52, s41
	s_add_u32 s40, s7, s64
	s_addc_u32 s41, s12, 0
	s_lshr_b32 s7, s66, 2
	v_bfe_u32 v1, v0, 2, 4
	v_mov_b32_e32 v235, v201
	v_and_or_b32 v1, s7, 48, v1
	v_lshl_add_u64 v[10:11], s[42:43], 0, v[234:235]
	s_lshl_b32 s12, s65, 4
	v_lshlrev_b32_e32 v200, 10, v1
	v_lshl_add_u64 v[226:227], v[10:11], 0, s[12:13]
	v_lshl_add_u64 v[10:11], s[40:41], 0, v[200:201]
	s_and_b32 s12, s7, 0x3fffffc0
	v_lshl_add_u64 v[10:11], v[10:11], 0, s[12:13]
	s_lshl_b32 s12, s65, 10
	s_cmp_lg_u32 0, -1
	s_cselect_b32 s7, 0, 0
	global_load_dwordx4 v[2:5], v[6:7], off offset:16
	s_nop 0
	global_load_dwordx4 v[6:9], v[6:7], off
	s_and_b32 s88, s63, 63
	s_lshl_b32 s88, s88, 14
	s_lshl_b32 s89, s45, 2
	s_add_i32 s88, s88, s89
	s_addk_i32 s88, 0x200
	v_mov_b32_e32 v231, s88
	global_load_dword v231, v231, s[86:87]
	v_mov_b32_e32 v215, v201
	s_add_i32 s67, s12, s7
	s_mov_b32 s7, m0
	s_mov_b32 m0, s67
	s_nop 0
	global_load_lds_dwordx4 v[226:227], off
	s_mov_b32 m0, s7
	v_lshl_add_u64 v[228:229], v[10:11], 0, v[214:215]
	s_add_i32 s68, s67, 0x6000
	s_mov_b32 s7, m0
	s_mov_b32 m0, s68
	s_nop 0
	global_load_lds_dwordx4 v[228:229], off
	s_mov_b32 m0, s7
	v_lshl_add_u64 v[10:11], v[226:227], 0, s[16:17]
	s_add_i32 s7, s67, 0x2000
	s_mov_b32 s40, m0
	s_mov_b32 m0, s7
	s_nop 0
	global_load_lds_dwordx4 v[10:11], off
	s_mov_b32 m0, s40
	global_load_dwordx4 v[126:129], v255, s[8:9]
	global_load_dwordx4 v[122:125], v255, s[8:9] offset:32
	global_load_dwordx4 v[118:121], v255, s[8:9] offset:64
	global_load_dwordx4 v[114:117], v255, s[8:9] offset:96
	v_lshl_add_u64 v[10:11], v[226:227], 0, s[20:21]
	s_add_i32 s7, s67, 0x4000
	s_mov_b32 s8, m0
	s_mov_b32 m0, s7
	s_nop 0
	global_load_lds_dwordx4 v[10:11], off
	s_mov_b32 m0, s8
	v_add_u32_e32 v1, 0, v202
	v_add_u32_e32 v1, 0x14800, v1
	v_mov_b32_e32 v212, v213
	s_waitcnt vmcnt(4)
	v_add_f32_e32 v231, v237, v231
	v_sub_f32_e32 v2, v2, v231
	v_sub_f32_e32 v3, v3, v231
	v_sub_f32_e32 v4, v4, v231
	v_sub_f32_e32 v5, v5, v231
	v_sub_f32_e32 v6, v6, v231
	v_sub_f32_e32 v7, v7, v231
	v_sub_f32_e32 v8, v8, v231
	v_sub_f32_e32 v9, v9, v231
	ds_write_b128 v1, v[6:9]
	ds_write_b128 v1, v[2:5] offset:16
	s_and_saveexec_b64 s[8:9], s[18:19]
	s_cbranch_execz .LBB0_351
	s_mov_b64 s[42:43], exec
	v_mbcnt_lo_u32_b32 v1, s42, 0
	v_mbcnt_hi_u32_b32 v1, s43, v1
	v_cmp_eq_u32_e32 vcc, 0, v1
	s_and_saveexec_b64 s[40:41], vcc
	s_cbranch_execz .LBB0_350
	s_bcnt1_i32_b64 s7, s[42:43]
	v_mov_b32_e32 v2, s7
	global_atomic_add v2, v201, v2, s[14:15] sc0
